# strip_all + SB: folded 32 canonicalising v_max per tile into the relu max
# speedup vs baseline: 1.0138x; 1.0047x over previous
; __device__ __forceinline__ float ex2(float x) { return __builtin_amdgcn_exp2f(x); }
; __device__ __forceinline__ float lg2(float x) { return __builtin_amdgcn_logf(x); }
; #define ATT_LOADV(vf, vbuf) do { _Pragma("unroll") for (int s4 = 0; s4 < 4; ++s4) _Pragma("unroll") for (int db = 0; db < 2; ++db) { const LAS unsigned char* vp = (vbuf) + voff + 16 * s4 * KP + 64 * db; vf[s4][db] = tr8(vp, vp + 8 * KP); } \
;         __builtin_amdgcn_sched_barrier(0); } while (0)
; __device__ __forceinline__ void p_attn_sb(const Params& P, LAS unsigned char* lds) {
;     ...
;                 ATT_QK_ACC(z, kbuf);
;                 h16x8 vf[4][2]; ATT_LOADV(vf, vbuf);
; #pragma unroll
;                 for (int kb = 0; kb < 2; ++kb)
; #pragma unroll
;                     for (int i = 0; i < 16; ++i) { const float zz = z[kb][i]; const float e = ex2(-fabsf(zz)); lk[kb][i] = -(fmaxf(zz, 0.f) + lg2(1.0f + e)); }
.LBB0_404:
	s_mul_i32 s12, s41, 0x2400
	v_add_u32_e32 v1, s12, v176
	ds_read_b128 v[2:5], v1
	ds_read_b128 v[6:9], v1 offset:32
	ds_read_b128 v[10:13], v1 offset:64
	ds_read_b128 v[82:85], v1 offset:96
	ds_read_b128 v[86:89], v1 offset:4608
	ds_read_b128 v[90:93], v1 offset:4640
	ds_read_b128 v[94:97], v1 offset:4672
	ds_read_b128 v[130:133], v1 offset:4704
	s_waitcnt vmcnt(5) lgkmcnt(3)
	v_mfma_f32_32x32x16_f16 v[66:81], v[86:89], v[106:109], v[66:81]
	v_add_u32_e32 v1, s12, v177
	s_waitcnt vmcnt(4) lgkmcnt(2)
	v_mfma_f32_32x32x16_f16 v[66:81], v[90:93], v[110:113], v[66:81]
	s_waitcnt vmcnt(3) lgkmcnt(1)
	v_mfma_f32_32x32x16_f16 v[66:81], v[94:97], v[114:117], v[66:81]
	v_mfma_f32_32x32x16_f16 v[50:65], v[2:5], v[106:109], v[50:65]
	s_waitcnt vmcnt(2) lgkmcnt(0)
	v_mfma_f32_32x32x16_f16 v[66:81], v[130:133], v[118:121], v[66:81]
	ds_read_b64_tr_b16 v[158:159], v1 offset:18432
	ds_read_b64_tr_b16 v[160:161], v1 offset:19584
	ds_read_b64_tr_b16 v[146:147], v1 offset:18496
	ds_read_b64_tr_b16 v[148:149], v1 offset:19648
	ds_read_b64_tr_b16 v[154:155], v1 offset:20736
	ds_read_b64_tr_b16 v[156:157], v1 offset:21888
	ds_read_b64_tr_b16 v[138:139], v1 offset:20800
	ds_read_b64_tr_b16 v[140:141], v1 offset:21952
	ds_read_b64_tr_b16 v[150:151], v1 offset:23040
	ds_read_b64_tr_b16 v[152:153], v1 offset:24192
	ds_read_b64_tr_b16 v[134:135], v1 offset:23104
	ds_read_b64_tr_b16 v[136:137], v1 offset:24256
	ds_read_b64_tr_b16 v[142:143], v1 offset:25344
	ds_read_b64_tr_b16 v[144:145], v1 offset:26496
	ds_read_b64_tr_b16 v[130:131], v1 offset:25408
	ds_read_b64_tr_b16 v[132:133], v1 offset:26560
	v_mfma_f32_32x32x16_f16 v[50:65], v[6:9], v[110:113], v[50:65]
	v_mfma_f32_32x32x16_f16 v[50:65], v[10:13], v[114:117], v[50:65]
	v_mfma_f32_32x32x16_f16 v[50:65], v[82:85], v[118:121], v[50:65]
	s_nop 11
	v_exp_f32_e64 v1, -|v50|
	v_max_f32_e32 v2, 0, v50
	v_exp_f32_e64 v3, -|v51|
	v_add_f32_e32 v1, 1.0, v1
	v_log_f32_e32 v1, v1
	v_max_f32_e32 v10, 0, v51
	v_add_f32_e32 v3, 1.0, v3
	v_add_f32_e32 v169, v2, v1
	v_exp_f32_e64 v1, -|v52|
	v_max_f32_e32 v11, 0, v52
	v_exp_f32_e64 v2, -|v53|
	v_add_f32_e32 v1, 1.0, v1
	v_log_f32_e32 v85, v1
	v_max_f32_e32 v82, 0, v53
	v_add_f32_e32 v1, 1.0, v2
	v_exp_f32_e64 v2, -|v54|
	v_log_f32_e32 v86, v1
	v_max_f32_e32 v83, 0, v54
	v_add_f32_e32 v1, 1.0, v2
	v_exp_f32_e64 v2, -|v55|
	v_log_f32_e32 v87, v1
	v_max_f32_e32 v14, 0, v55
	v_add_f32_e32 v1, 1.0, v2
	v_exp_f32_e64 v2, -|v56|
	v_log_f32_e32 v88, v1
	v_max_f32_e32 v15, 0, v56
	v_add_f32_e32 v1, 1.0, v2
	v_exp_f32_e64 v2, -|v57|
	v_log_f32_e32 v89, v1
	v_max_f32_e32 v8, 0, v57
	v_add_f32_e32 v1, 1.0, v2
	v_exp_f32_e64 v2, -|v58|
	v_log_f32_e32 v90, v1
	v_max_f32_e32 v9, 0, v58
	v_add_f32_e32 v1, 1.0, v2
	v_exp_f32_e64 v2, -|v59|
	v_log_f32_e32 v91, v1
	v_max_f32_e32 v6, 0, v59
	v_add_f32_e32 v1, 1.0, v2
	v_exp_f32_e64 v2, -|v60|
	v_log_f32_e32 v92, v1
	v_max_f32_e32 v7, 0, v60
	v_add_f32_e32 v1, 1.0, v2
	v_exp_f32_e64 v2, -|v61|
	v_log_f32_e32 v93, v1
	v_max_f32_e32 v4, 0, v61
	v_add_f32_e32 v1, 1.0, v2
	v_exp_f32_e64 v2, -|v62|
	v_log_f32_e32 v84, v3
	v_exp_f32_e64 v3, -|v63|
	v_log_f32_e32 v94, v1
	v_max_f32_e32 v5, 0, v62
	v_add_f32_e32 v1, 1.0, v2
	v_log_f32_e32 v95, v1
	v_max_f32_e32 v2, 0, v63
	v_add_f32_e32 v1, 1.0, v3
	v_log_f32_e32 v12, v1
	v_exp_f32_e64 v1, -|v64|
	v_exp_f32_e64 v96, -|v65|
	v_max_f32_e32 v97, 0, v65
	v_add_f32_e32 v1, 1.0, v1
	v_log_f32_e32 v13, v1
	v_add_f32_e32 v1, 1.0, v96
	v_log_f32_e32 v1, v1
	v_exp_f32_e64 v96, -|v66|
	v_exp_f32_e64 v190, -|v73|
	v_add_f32_e32 v171, v97, v1
	v_add_f32_e32 v1, 1.0, v96
	v_log_f32_e32 v1, v1
	v_exp_f32_e64 v97, -|v67|
	v_max_f32_e32 v96, 0, v66
	v_add_f32_e32 v96, v96, v1
	v_max_f32_e32 v178, 0, v67
	v_add_f32_e32 v1, 1.0, v97
	v_exp_f32_e64 v97, -|v68|
	v_log_f32_e32 v180, v1
	v_max_f32_e32 v179, 0, v68
	v_add_f32_e32 v1, 1.0, v97
	v_exp_f32_e64 v97, -|v69|
	v_log_f32_e32 v181, v1
	v_max_f32_e32 v182, 0, v69
	v_add_f32_e32 v1, 1.0, v97
	v_exp_f32_e64 v97, -|v70|
	v_log_f32_e32 v184, v1
	v_max_f32_e32 v183, 0, v70
	v_add_f32_e32 v1, 1.0, v97
	v_exp_f32_e64 v97, -|v71|
	v_log_f32_e32 v185, v1
	v_max_f32_e32 v186, 0, v71
	v_add_f32_e32 v1, 1.0, v97
	v_log_f32_e32 v188, v1
	v_exp_f32_e64 v1, -|v72|
	v_max_f32_e32 v187, 0, v72
	v_exp_f32_e64 v97, -|v74|
	v_add_f32_e32 v1, 1.0, v1
	v_log_f32_e32 v189, v1
	v_add_f32_e32 v1, 1.0, v190
	v_log_f32_e32 v1, v1
	v_max_f32_e32 v190, 0, v73
	v_pk_add_f32 v[178:179], v[178:179], v[180:181]
	v_add_f32_e32 v191, v190, v1
	v_add_f32_e32 v1, 1.0, v97
	v_log_f32_e32 v1, v1
	v_exp_f32_e64 v190, -|v75|
	v_max_f32_e32 v97, 0, v74
	v_add_f32_e32 v192, v97, v1
	v_exp_f32_e64 v97, -|v76|
	v_max_f32_e32 v194, 0, v75
	v_add_f32_e32 v1, 1.0, v190
	v_log_f32_e32 v196, v1
	v_max_f32_e32 v195, 0, v76
	v_add_f32_e32 v1, 1.0, v97
	v_exp_f32_e64 v97, -|v77|
	v_log_f32_e32 v197, v1
	v_max_f32_e32 v198, 0, v77
	v_add_f32_e32 v1, 1.0, v97
	v_exp_f32_e64 v97, -|v78|
	v_log_f32_e32 v200, v1
	v_max_f32_e32 v199, 0, v78
	v_add_f32_e32 v1, 1.0, v97
	v_exp_f32_e64 v97, -|v79|
	v_log_f32_e32 v201, v1
	v_max_f32_e32 v202, 0, v79
	v_add_f32_e32 v1, 1.0, v97
	v_exp_f32_e64 v97, -|v81|
	v_log_f32_e32 v204, v1
	v_exp_f32_e64 v1, -|v80|
	v_pk_add_f32 v[180:181], v[182:183], v[184:185]
	v_add_f32_e32 v97, 1.0, v97
	v_log_f32_e32 v97, v97
	v_add_f32_e32 v1, 1.0, v1
	v_log_f32_e32 v205, v1
	v_max_f32_e32 v1, 0, v81
	v_add_f32_e32 v207, v1, v97
	v_pk_add_f32 v[182:183], v[186:187], v[188:189]
	v_mov_b32_e32 v97, v178
	v_pk_add_f32 v[10:11], v[10:11], v[84:85]
	v_mov_b32_e32 v85, v52
	v_pk_add_f32 v[82:83], v[82:83], v[86:87]
	v_mov_b32_e32 v52, v53
	v_mov_b32_e32 v53, v54
	v_max_f32_e32 v3, 0, v64
; __device__ __forceinline__ float ex2(float x) { return __builtin_amdgcn_exp2f(x); }
; #define MFMA32(a, b, c) __builtin_amdgcn_mfma_f32_32x32x16_f16((a), (b), (c), 0, 0, 0)
; __device__ __forceinline__ void p_attn_sb(const Params& P, LAS unsigned char* lds) {
;     ...
;                 const h16x8 x00 = pack8(lk[0], 0), x01 = pack8(lk[0], 1), x10 = pack8(lk[1], 0), x11 = pack8(lk[1], 1);
;                 const float lk00 = lk[0][0], lb00 = z[0][0] + lk00;
; #pragma unroll
;                 for (int i = 0; i < 16; ++i) { z[0][i] += lk[0][i]; z[1][i] += lk[1][i]; }
;                 z[0][0] = 0.f;
;                 f32x16 y0 = MFMA32(uf[0], x00, z[0]), y1 = MFMA32(uf[0], x10, z[1]);
;                 y0 = MFMA32(uf[1], x01, y0); y1 = MFMA32(uf[1], x11, y1); y0 = MFMA32(ones, x10, y0); y0 = MFMA32(ones, x11, y0);
;                 float tot = y0[0] + lk00;
;                 { auto rr_ = __builtin_amdgcn_permlane32_swap(__float_as_uint(tot), __float_as_uint(tot), false, false); tot = __uint_as_float(rr_[0]); }
;                 y0[0] += lb00;
; #pragma unroll
;                 for (int i = 0; i < 16; ++i) { z[0][i] = ex2(y0[i] + carry); z[1][i] = ex2(y1[i] + carry); }
	v_cvt_f16_f32_e64 v1, -v96
	v_cvt_pk_f16_f32 v209, v180, v181
	v_pk_add_f32 v[184:185], v[194:195], v[196:197]
	v_pk_add_f32 v[186:187], v[198:199], v[200:201]
	v_pk_add_f32 v[66:67], v[66:67], v[96:97] neg_lo:[0,1] neg_hi:[0,1]
	v_pk_mov_b32 v[96:97], v[178:179], v[180:181] op_sel:[1,0]
	v_pk_add_f32 v[86:87], v[52:53], v[82:83] neg_lo:[0,1] neg_hi:[0,1]
	v_pk_mov_b32 v[52:53], v[180:181], v[182:183] op_sel:[1,0]
	v_pk_add_f32 v[180:181], v[6:7], v[92:93]
	v_mov_b32_e32 v6, v59
	v_mov_b32_e32 v7, v60
	v_max_f32_e32 v203, 0, v80
	v_cvt_pk_f16_f32 v208, v178, v179
	v_cvt_pk_f16_f32 v194, v184, v185
	v_pk_add_f32 v[178:179], v[8:9], v[90:91]
	v_mov_b32_e32 v9, v58
	v_mov_b32_e32 v193, v184
	v_pk_add_f32 v[58:59], v[6:7], v[180:181] neg_lo:[0,1] neg_hi:[0,1]
	v_pk_mov_b32 v[6:7], v[184:185], v[186:187] op_sel:[1,0]
	v_pk_add_f32 v[184:185], v[2:3], v[12:13]
	v_mov_b32_e32 v2, v63
	v_mov_b32_e32 v3, v64
	v_cvt_pk_f16_f32 v210, v182, v183
	v_pk_add_f32 v[188:189], v[202:203], v[204:205]
	v_mov_b32_e32 v84, v51
	v_pk_add_f32 v[70:71], v[70:71], v[52:53] neg_lo:[0,1] neg_hi:[0,1]
	v_pk_add_f32 v[52:53], v[14:15], v[88:89]
	v_mov_b32_e32 v14, v55
	v_mov_b32_e32 v15, v56
	v_mov_b32_e32 v190, v183
	v_mov_b32_e32 v8, v57
	v_pk_add_f32 v[182:183], v[4:5], v[94:95]
	v_mov_b32_e32 v4, v61
	v_mov_b32_e32 v5, v62
	v_pk_add_f32 v[62:63], v[2:3], v[184:185] neg_lo:[0,1] neg_hi:[0,1]
	v_pk_add_f32 v[84:85], v[84:85], v[10:11] neg_lo:[0,1] neg_hi:[0,1]
	v_pk_add_f32 v[88:89], v[14:15], v[52:53] neg_lo:[0,1] neg_hi:[0,1]
	v_pk_add_f32 v[8:9], v[8:9], v[178:179] neg_lo:[0,1] neg_hi:[0,1]
	v_pk_add_f32 v[60:61], v[4:5], v[182:183] neg_lo:[0,1] neg_hi:[0,1]
	v_pk_mov_b32 v[4:5], v[186:187], v[188:189] op_sel:[1,0]
	v_sub_f32_e32 v15, v65, v171
	v_mov_b32_e32 v14, v63
	v_pk_add_f32 v[68:69], v[68:69], v[96:97] neg_lo:[0,1] neg_hi:[0,1]
	v_pk_add_f32 v[76:77], v[76:77], v[6:7] neg_lo:[0,1] neg_hi:[0,1]
	v_pk_add_f32 v[78:79], v[78:79], v[4:5] neg_lo:[0,1] neg_hi:[0,1]
	v_cvt_pk_f16_f32 v55, -v53, -v178
	v_cvt_pk_f16_f32 v54, -v83, -v52
	v_cvt_pk_f16_f32 v53, -v11, -v82
	v_cvt_pk_f16_f32 v52, -v169, -v10
	v_pack_b32_f16 v56, v1, -v208
	v_mov_b32_e32 v1, v84
	v_mov_b32_e32 v2, v85
	v_mov_b32_e32 v3, v86
	v_mov_b32_e32 v4, v87
	v_mov_b32_e32 v5, v88
	v_mov_b32_e32 v6, v89
	v_mov_b32_e32 v7, v8
	v_mov_b32_e32 v8, v9
	v_mov_b32_e32 v9, v58
	v_mov_b32_e32 v10, v59
	v_mov_b32_e32 v11, v60
	v_mov_b32_e32 v12, v61
	v_mov_b32_e32 v13, v62
	v_mov_b64_e32 v[96:97], v[14:15]
	v_mov_b64_e32 v[94:95], v[12:13]
	v_mov_b64_e32 v[92:93], v[10:11]
	v_mov_b64_e32 v[90:91], v[8:9]
	v_mov_b64_e32 v[88:89], v[6:7]
	v_mov_b64_e32 v[86:87], v[4:5]
	v_mov_b64_e32 v[84:85], v[2:3]
	v_mov_b64_e32 v[82:83], v[0:1]
	v_cvt_f16_f32_e64 v211, -v191
	v_xor_b32_sdwa v51, s78, v208 dst_sel:DWORD dst_unused:UNUSED_PAD src0_sel:DWORD src1_sel:WORD_1
	v_mfma_f32_32x32x16_f16 v[82:97], v[98:101], v[52:55], v[82:97]
	v_xor_b32_e32 v1, 0x8000, v209
	v_perm_b32 v57, v1, v51, s79
	v_xor_b32_sdwa v1, s78, v209 dst_sel:DWORD dst_unused:UNUSED_PAD src0_sel:DWORD src1_sel:WORD_1
	v_xor_b32_e32 v2, 0x8000, v210
	v_perm_b32 v58, v2, v1, s79
	v_xor_b32_sdwa v1, s78, v210 dst_sel:DWORD dst_unused:UNUSED_PAD src0_sel:DWORD src1_sel:WORD_1
	v_cvt_pk_f16_f32 v195, v186, v187
	v_perm_b32 v59, v211, v1, s79
	v_cvt_f16_f32_e64 v1, -v207
	v_cvt_pk_f16_f32 v4, -v183, -v184
	v_cvt_pk_f16_f32 v3, -v181, -v182
	v_cvt_pk_f16_f32 v2, -v179, -v180
	v_cvt_pk_f16_f32 v5, -v185, -v171
	v_cvt_pk_f16_f32 v196, v188, v189
	v_xor_b32_sdwa v7, s78, v194 dst_sel:DWORD dst_unused:UNUSED_PAD src0_sel:DWORD src1_sel:WORD_1
	v_mfma_f32_32x32x16_f16 v[82:97], v[102:105], v[2:5], v[82:97]
	v_xor_b32_e32 v2, 0x8000, v195
	v_perm_b32 v7, v2, v7, s79
	v_xor_b32_sdwa v2, s78, v195 dst_sel:DWORD dst_unused:UNUSED_PAD src0_sel:DWORD src1_sel:WORD_1
	v_xor_b32_e32 v3, 0x8000, v196
	v_perm_b32 v8, v3, v2, s79
	v_xor_b32_sdwa v2, s78, v196 dst_sel:DWORD dst_unused:UNUSED_PAD src0_sel:DWORD src1_sel:WORD_1
	s_mov_b32 s49, s48
	v_perm_b32 v9, v1, v2, s79
	s_mov_b32 s50, s48
	s_mov_b32 s51, s48
	v_mov_b64_e32 v[2:3], s[48:49]
	v_mov_b64_e32 v[4:5], s[50:51]
	v_mov_b32_e32 v206, v189
	v_pk_add_f32 v[72:73], v[72:73], v[190:191] neg_lo:[0,1] neg_hi:[0,1]
	v_pk_add_f32 v[74:75], v[74:75], v[192:193] neg_lo:[0,1] neg_hi:[0,1]
	v_pk_add_f32 v[80:81], v[80:81], v[206:207] neg_lo:[0,1] neg_hi:[0,1]
	v_mfma_f32_32x32x16_f16 v[82:97], v[2:5], v[56:59], v[82:97]
	v_cvt_f16_f32_e64 v212, -v192
	v_sub_f32_e32 v1, v50, v169
	s_mov_b32 s12, 0xc3170000
	v_pack_b32_f16 v6, v212, -v194
	v_mfma_f32_32x32x16_f16 v[66:81], v[98:101], v[56:59], v[66:81]
	s_nop 0
	v_mfma_f32_32x32x16_f16 v[66:81], v[102:105], v[6:9], v[66:81]
	v_mfma_f32_32x32x16_f16 v[82:97], v[2:5], v[6:9], v[82:97]
	s_nop 10
	v_add_f32_e32 v4, v167, v68
	v_add_f32_e32 v5, v167, v70
	v_exp_f32_e32 v8, v4
	v_exp_f32_e32 v11, v5
	v_add_f32_e32 v2, v167, v66
	v_add_f32_e32 v3, v167, v67
	v_exp_f32_e32 v6, v2
	v_add_f32_e32 v4, v167, v85
	v_add_f32_e32 v5, v167, v87
	v_add_f32_e32 v1, v1, v82
	v_exp_f32_e32 v9, v4
	v_add_f32_e32 v4, v167, v69
	v_exp_f32_e32 v12, v5
	v_add_f32_e32 v5, v167, v71
	v_add_f32_e32 v1, v167, v1
	v_add_f32_e32 v2, v167, v83
	v_exp_f32_e32 v7, v3
	v_add_f32_e32 v3, v167, v84
	v_exp_f32_e32 v10, v4
	v_add_f32_e32 v4, v167, v86
	v_exp_f32_e32 v13, v5
	v_add_f32_e32 v5, v167, v88
	v_add_f32_e32 v14, v167, v89
	v_exp_f32_e32 v1, v1
	v_exp_f32_e32 v2, v2
	v_exp_f32_e32 v3, v3
	v_exp_f32_e32 v4, v4
	v_exp_f32_e32 v5, v5
	v_exp_f32_e32 v14, v14
	v_cvt_pk_f16_f32 v3, v3, v9
	v_cvt_pk_f16_f32 v4, v4, v12
	v_cvt_pk_f16_f32 v2, v1, v2
	v_cvt_pk_f16_f32 v5, v5, v14
	v_add_f32_e32 v15, v167, v90
	v_add_f32_e32 v50, v167, v91
	s_waitcnt lgkmcnt(14)
; __device__ __forceinline__ float ex2(float x) { return __builtin_amdgcn_exp2f(x); }
; #define ATT_PV(o, s, vf) do { _Pragma("unroll") for (int s4 = 0; s4 < 4; ++s4) { const h16x8 pf = pack8(s[s4 >> 1], s4 & 1); \
;         _Pragma("unroll") for (int db = 0; db < 2; ++db) o[db] = MFMA32(vf[s4][db], pf, o[db]); } } while (0)
; __device__ __forceinline__ void p_attn_sb(const Params& P, LAS unsigned char* lds) {
;     ...
;                 for (int i = 0; i < 16; ++i) { z[0][i] = ex2(y0[i] + carry); z[1][i] = ex2(y1[i] + carry); }
;                 carry += tot;
;                 ATT_PV(o, z, vf);
;                 wdone = (__ballot(carry < -151.0f) == ~0ull);
	v_mfma_f32_32x32x16_f16 v[34:49], v[158:161], v[2:5], v[34:49]
	v_add_f32_e32 v51, v167, v92
	v_add_f32_e32 v52, v167, v93
	v_add_f32_e32 v1, v167, v94
	v_add_f32_e32 v9, v167, v95
	v_add_f32_e32 v12, v167, v96
	v_add_f32_e32 v14, v167, v97
	v_exp_f32_e32 v15, v15
	s_waitcnt lgkmcnt(12)
	v_mfma_f32_32x32x16_f16 v[18:33], v[146:149], v[2:5], v[18:33]
	v_exp_f32_e32 v51, v51
	v_exp_f32_e32 v1, v1
	v_exp_f32_e32 v12, v12
	v_exp_f32_e32 v14, v14
	v_exp_f32_e32 v2, v9
	v_exp_f32_e32 v3, v52
	v_exp_f32_e32 v9, v50
	v_cvt_pk_f16_f32 v5, v12, v14
	v_cvt_pk_f16_f32 v4, v1, v2
	v_cvt_pk_f16_f32 v3, v51, v3
	v_cvt_pk_f16_f32 v2, v15, v9
	v_add_f32_e32 v1, v167, v72
	v_add_f32_e32 v9, v167, v73
	s_waitcnt lgkmcnt(10)
	v_mfma_f32_32x32x16_f16 v[34:49], v[154:157], v[2:5], v[34:49]
	v_exp_f32_e32 v1, v1
	v_exp_f32_e32 v9, v9
	v_add_f32_e32 v12, v167, v74
	v_add_f32_e32 v14, v167, v75
	v_add_f32_e32 v50, v167, v77
	v_exp_f32_e32 v12, v12
	s_waitcnt lgkmcnt(8)
	v_mfma_f32_32x32x16_f16 v[18:33], v[138:141], v[2:5], v[18:33]
	v_add_f32_e32 v2, v167, v76
	v_exp_f32_e32 v15, v2
	v_cvt_pk_f16_f32 v5, v1, v9
	v_cvt_pk_f16_f32 v4, v11, v13
	v_cvt_pk_f16_f32 v3, v8, v10
	v_cvt_pk_f16_f32 v2, v6, v7
	v_add_f32_e32 v1, v167, v78
	v_add_f32_e32 v6, v167, v79
	s_waitcnt lgkmcnt(6)
	v_mfma_f32_32x32x16_f16 v[34:49], v[150:153], v[2:5], v[34:49]
	v_add_f32_e32 v7, v167, v80
	v_add_f32_e32 v8, v167, v81
	v_exp_f32_e32 v1, v1
	v_exp_f32_e32 v7, v7
	v_exp_f32_e32 v8, v8
	s_waitcnt lgkmcnt(4)
	v_mfma_f32_32x32x16_f16 v[18:33], v[134:137], v[2:5], v[18:33]
	v_exp_f32_e32 v2, v6
	v_exp_f32_e32 v3, v50
	v_exp_f32_e32 v6, v14
	v_cvt_pk_f16_f32 v5, v7, v8
	v_cvt_pk_f16_f32 v4, v1, v2
	v_cvt_pk_f16_f32 v3, v15, v3
	v_cvt_pk_f16_f32 v2, v12, v6
	v_sub_f32_e32 v1, v82, v169
	v_mov_b32_e32 v6, v1
	s_waitcnt lgkmcnt(2)
	v_mfma_f32_32x32x16_f16 v[34:49], v[142:145], v[2:5], v[34:49]
	v_permlane32_swap_b32_e32 v1, v6
	v_add_f32_e32 v167, v167, v1
	v_cmp_gt_f32_e32 vcc, s12, v167
	s_cmp_eq_u64 vcc, -1
	s_cselect_b64 s[16:17], -1, 0
	s_waitcnt lgkmcnt(0)
	v_mfma_f32_32x32x16_f16 v[18:33], v[130:133], v[2:5], v[18:33]
